# scan waves: operand-load burst placed after the partial-sum adds (before the first DPP level)
# speedup vs baseline: 1.0076x; 1.0008x over previous
; __device__ __forceinline__ void phase_scan(const Params& p, LAS unsigned char* lds) {
;     ...
;                     const LAS float* sR = OPS + (n & 1) * SET_F + j0; const LAS float* sW = sR + 2048; const LAS float* sK = sW + 2048; const LAS float* sA = sK + 2048; const LAS float* sB = sA + 2048; const LAS float* sV = OPS + (n & 1) * SET_F + 10240;
;                     LAS float* sY = sYb + (n & 1) * 512;
;                     f32x4 a_ = *(const LAS f32x4*)(sA), w_ = *(const LAS f32x4*)(sW), b_ = *(const LAS f32x4*)(sB);
;                     f32x4 k_ = *(const LAS f32x4*)(sK), r_ = *(const LAS f32x4*)(sR);
;                     f32x4 vq[4];
; #pragma unroll
;                     for (int u = 0; u < 4; ++u) vq[u] = *(const LAS f32x4*)(sV + srow * 32 + 4 * u);
;                     f32x4 rp = r_;
; #pragma unroll
;                     for (int hb = 0; hb < 2; ++hb) {
;                         f32x4 vn[4];
; #pragma unroll
;                         for (int u = 0; u < 4; ++u) vn[u] = *(const LAS f32x4*)(sV + srow * 32 + ((16 * (hb + 1)) & 31) + 4 * u);
; #pragma unroll
;                         for (int u16 = 0; u16 < 16; ++u16) {
;                             const int s = 16 * hb + u16;
;                             const int sn = (s + 1) & 31;
;                             const f32x4 a_n = *(const LAS f32x4*)(sA + sn * 64), w_n = *(const LAS f32x4*)(sW + sn * 64), b_n = *(const LAS f32x4*)(sB + sn * 64);
;                             const f32x4 k_n = *(const LAS f32x4*)(sK + sn * 64), r_n = *(const LAS f32x4*)(sR + sn * 64);
;                             const float v = vq[u16 >> 2][u16 & 3];
;                             const f32x2 vv = {v, v};
;                             f32x2 pp = S01 * (f32x2){a_[0], a_[1]}; pp = S23 * (f32x2){a_[2], a_[3]} + pp;
;                             f32x2 yy = S01 * (f32x2){rp[0], rp[1]}; yy = S23 * (f32x2){rp[2], rp[3]} + yy;
;                             float sa = pp[0] + pp[1], y = yy[0] + yy[1];
;                             sa += dpp_f<0xB1>(sa); y += dpp_f<0xB1>(y);
;                             sa += dpp_f<0x4E>(sa); y += dpp_f<0x4E>(y);
;                             sa += dpp_f<0x141>(sa); y += dpp_f<0x141>(y);
;                             sa += dpp_f<0x140>(sa); y += dpp_f<0x140>(y);
;                             sY[((s - 1) & 31) * 16 + srow] = y;
;                             const f32x2 sv = {sa, sa};
.Lscan_wave_top:
	s_mov_b64 s[54:55], 0
	s_cmp_lt_i32 s81, 0
	s_cbranch_scc1 .LBB0_603
	s_setprio 1
	s_and_b32 s14, s81, 1
	s_mul_i32 s15, s14, 0xa800
	s_add_i32 s15, s15, 0x8800
	v_add_u32_e32 v124, s15, v178
	v_add_u32_e32 v125, s15, v179
	s_cmp_eq_u32 s81, 0
	s_cselect_b32 s14, 0xc000c000, -1
	s_mov_b32 s15, s14
	v_pk_mul_f32 v[114:115], v[166:167], v[22:23]
	v_pk_mul_f32 v[116:117], v[166:167], v[18:19]
	v_pk_fma_f32 v[114:115], v[164:165], v[24:25], v[114:115]
	v_pk_fma_f32 v[116:117], v[164:165], v[20:21], v[116:117]
	v_add_f32_e32 v122, v114, v115
	v_pk_mul_f32 v[118:119], v[110:111], v[34:35] op_sel:[1,0]
	v_add_f32_e32 v214, v116, v117
	ds_read_b128 v[14:17], v124 offset:16384
	ds_read_b128 v[6:9], v124 offset:8192
	ds_read_b128 v[10:13], v124 offset:32768
	ds_read_b128 v[18:21], v124 offset:0
	ds_read_b128 v[2:5], v124 offset:24576
	ds_read_b128 v[82:85], v125 offset:40960
	v_add_f32_dpp v122, v122, v122 quad_perm:[1,0,3,2] row_mask:0xf bank_mask:0xf bound_ctrl:1
	v_pk_mul_f32 v[120:121], v[110:111], v[36:37] op_sel:[1,0]
	v_add_f32_dpp v204, v204, v204 row_mirror row_mask:0xf bank_mask:0xf bound_ctrl:1
	v_add_f32_dpp v122, v122, v122 quad_perm:[2,3,0,1] row_mask:0xf bank_mask:0xf bound_ctrl:1
	v_pk_fma_f32 v[166:167], v[166:167], v[26:27], v[118:119]
	v_add_f32_dpp v204, v212, v212 row_mirror row_mask:0xf bank_mask:0xc bound_ctrl:1
	v_add_f32_dpp v122, v122, v122 row_half_mirror row_mask:0xf bank_mask:0xf bound_ctrl:1
	v_pk_fma_f32 v[164:165], v[164:165], v[28:29], v[120:121]
	v_add_f32_dpp v205, v205, v205 row_mirror row_mask:0xf bank_mask:0xf bound_ctrl:1
	v_add_f32_dpp v122, v122, v122 row_mirror row_mask:0xf bank_mask:0xf bound_ctrl:1
	v_add_f32_dpp v205, v213, v213 row_mirror row_mask:0xf bank_mask:0xc bound_ctrl:1
	v_add_f32_dpp v206, v206, v206 row_mirror row_mask:0xf bank_mask:0xf bound_ctrl:1
	v_pk_fma_f32 v[166:167], v[30:31], v[122:123], v[166:167] op_sel_hi:[1,0,1]
	v_pk_fma_f32 v[164:165], v[32:33], v[122:123], v[164:165] op_sel_hi:[1,0,1]
	v_add_f32_dpp v206, v214, v214 row_mirror row_mask:0xf bank_mask:0xc bound_ctrl:1
	v_pk_mul_f32 v[114:115], v[166:167], v[42:43]
	v_pk_mul_f32 v[116:117], v[166:167], v[38:39]
	v_pk_fma_f32 v[114:115], v[164:165], v[44:45], v[114:115]
	v_pk_fma_f32 v[116:117], v[164:165], v[40:41], v[116:117]
	v_add_f32_e32 v122, v114, v115
	v_pk_mul_f32 v[118:119], v[112:113], v[54:55] op_sel_hi:[0,1]
	v_add_f32_e32 v215, v116, v117
	ds_read_b128 v[34:37], v124 offset:16640
	ds_read_b128 v[26:29], v124 offset:8448
	ds_read_b128 v[30:33], v124 offset:33024
	ds_read_b128 v[38:41], v124 offset:256
	ds_read_b128 v[22:25], v124 offset:24832
	v_add_f32_dpp v122, v122, v122 quad_perm:[1,0,3,2] row_mask:0xf bank_mask:0xf bound_ctrl:1
	v_pk_mul_f32 v[120:121], v[112:113], v[56:57] op_sel_hi:[0,1]
	v_add_f32_dpp v207, v207, v207 row_mirror row_mask:0xf bank_mask:0xf bound_ctrl:1
	v_add_f32_dpp v122, v122, v122 quad_perm:[2,3,0,1] row_mask:0xf bank_mask:0xf bound_ctrl:1
	v_pk_fma_f32 v[166:167], v[166:167], v[46:47], v[118:119]
	v_add_f32_dpp v207, v215, v215 row_mirror row_mask:0xf bank_mask:0xc bound_ctrl:1
	v_add_f32_dpp v122, v122, v122 row_half_mirror row_mask:0xf bank_mask:0xf bound_ctrl:1
	v_pk_fma_f32 v[164:165], v[164:165], v[48:49], v[120:121]
	s_nop 0
	v_add_f32_dpp v122, v122, v122 row_mirror row_mask:0xf bank_mask:0xf bound_ctrl:1
	s_nop 0
	v_pk_fma_f32 v[166:167], v[50:51], v[122:123], v[166:167] op_sel_hi:[1,0,1]
	v_pk_fma_f32 v[164:165], v[52:53], v[122:123], v[164:165] op_sel_hi:[1,0,1]
	v_pk_mul_f32 v[114:115], v[166:167], v[62:63]
	v_pk_mul_f32 v[116:117], v[166:167], v[58:59]
	v_pk_fma_f32 v[114:115], v[164:165], v[64:65], v[114:115]
	v_pk_fma_f32 v[116:117], v[164:165], v[60:61], v[116:117]
	v_add_f32_e32 v122, v114, v115
	v_pk_mul_f32 v[118:119], v[112:113], v[74:75] op_sel:[1,0]
	v_add_f32_e32 v216, v116, v117
	ds_read_b128 v[54:57], v124 offset:16896
	ds_read_b128 v[46:49], v124 offset:8704
	ds_read_b128 v[50:53], v124 offset:33280
	ds_read_b128 v[58:61], v124 offset:512
	ds_read_b128 v[42:45], v124 offset:25088
	v_add_f32_dpp v122, v122, v122 quad_perm:[1,0,3,2] row_mask:0xf bank_mask:0xf bound_ctrl:1
	v_pk_mul_f32 v[120:121], v[112:113], v[76:77] op_sel:[1,0]
	v_add_f32_dpp v208, v208, v208 row_mirror row_mask:0xf bank_mask:0xf bound_ctrl:1
	v_add_f32_dpp v122, v122, v122 quad_perm:[2,3,0,1] row_mask:0xf bank_mask:0xf bound_ctrl:1
	v_pk_fma_f32 v[166:167], v[166:167], v[66:67], v[118:119]
	v_add_f32_dpp v208, v216, v216 row_mirror row_mask:0xf bank_mask:0xc bound_ctrl:1
	v_add_f32_dpp v122, v122, v122 row_half_mirror row_mask:0xf bank_mask:0xf bound_ctrl:1
	v_pk_fma_f32 v[164:165], v[164:165], v[68:69], v[120:121]
	s_nop 0
	v_add_f32_dpp v122, v122, v122 row_mirror row_mask:0xf bank_mask:0xf bound_ctrl:1
	s_nop 0
	v_pk_fma_f32 v[166:167], v[70:71], v[122:123], v[166:167] op_sel_hi:[1,0,1]
	v_pk_fma_f32 v[164:165], v[72:73], v[122:123], v[164:165] op_sel_hi:[1,0,1]
	s_waitcnt lgkmcnt(11)
	v_pk_mul_f32 v[114:115], v[166:167], v[2:3]
	v_pk_mul_f32 v[116:117], v[166:167], v[78:79]
	v_pk_fma_f32 v[114:115], v[164:165], v[4:5], v[114:115]
	v_pk_fma_f32 v[116:117], v[164:165], v[80:81], v[116:117]
	v_add_f32_e32 v122, v114, v115
	s_waitcnt lgkmcnt(10)
; #define LAS __attribute__((address_space(3)))
; template <int CTRL> __device__ __forceinline__ float dpp_f(float x) { return __int_as_float(__builtin_amdgcn_update_dpp(0, __float_as_int(x), CTRL, 0xf, 0xf, false)); }
; __device__ __forceinline__ void phase_scan(const Params& p, LAS unsigned char* lds) {
;     ...
;                         for (int u16 = 0; u16 < 16; ++u16) {
;                             const int s = 16 * hb + u16;
;                             const int sn = (s + 1) & 31;
;                             const f32x4 a_n = *(const LAS f32x4*)(sA + sn * 64), w_n = *(const LAS f32x4*)(sW + sn * 64), b_n = *(const LAS f32x4*)(sB + sn * 64);
;                             const f32x4 k_n = *(const LAS f32x4*)(sK + sn * 64), r_n = *(const LAS f32x4*)(sR + sn * 64);
;                             const float v = vq[u16 >> 2][u16 & 3];
;                             const f32x2 vv = {v, v};
;                             f32x2 pp = S01 * (f32x2){a_[0], a_[1]}; pp = S23 * (f32x2){a_[2], a_[3]} + pp;
;                             f32x2 yy = S01 * (f32x2){rp[0], rp[1]}; yy = S23 * (f32x2){rp[2], rp[3]} + yy;
;                             float sa = pp[0] + pp[1], y = yy[0] + yy[1];
;                             sa += dpp_f<0xB1>(sa); y += dpp_f<0xB1>(y);
;                             sa += dpp_f<0x4E>(sa); y += dpp_f<0x4E>(y);
;                             sa += dpp_f<0x141>(sa); y += dpp_f<0x141>(y);
;                             sa += dpp_f<0x140>(sa); y += dpp_f<0x140>(y);
;                             sY[((s - 1) & 31) * 16 + srow] = y;
;                             const f32x2 sv = {sa, sa};
;                             S01 = S01 * (f32x2){w_[0], w_[1]} + vv * (f32x2){k_[0], k_[1]};
;                             S23 = S23 * (f32x2){w_[2], w_[3]} + vv * (f32x2){k_[2], k_[3]};
;                             S01 = sv * (f32x2){b_[0], b_[1]} + S01;
;                             S23 = sv * (f32x2){b_[2], b_[3]} + S23;
;                             rp = r_;
;                             a_ = a_n; w_ = w_n; b_ = b_n; k_ = k_n; r_ = r_n;
;                         }
	v_pk_mul_f32 v[118:119], v[82:83], v[14:15] op_sel_hi:[0,1]
	v_add_f32_e32 v217, v116, v117
	ds_read_b128 v[74:77], v124 offset:17152
	ds_read_b128 v[66:69], v124 offset:8960
	ds_read_b128 v[70:73], v124 offset:33536
	ds_read_b128 v[78:81], v124 offset:768
	ds_read_b128 v[62:65], v124 offset:25344
	v_add_f32_dpp v122, v122, v122 quad_perm:[1,0,3,2] row_mask:0xf bank_mask:0xf bound_ctrl:1
	v_pk_mul_f32 v[120:121], v[82:83], v[16:17] op_sel_hi:[0,1]
	v_add_f32_dpp v209, v209, v209 row_mirror row_mask:0xf bank_mask:0xf bound_ctrl:1
	v_add_f32_dpp v122, v122, v122 quad_perm:[2,3,0,1] row_mask:0xf bank_mask:0xf bound_ctrl:1
	v_pk_fma_f32 v[166:167], v[166:167], v[6:7], v[118:119]
	v_add_f32_dpp v209, v217, v217 row_mirror row_mask:0xf bank_mask:0xc bound_ctrl:1
	v_add_f32_dpp v122, v122, v122 row_half_mirror row_mask:0xf bank_mask:0xf bound_ctrl:1
	v_pk_fma_f32 v[164:165], v[164:165], v[8:9], v[120:121]
	s_nop 0
	v_add_f32_dpp v122, v122, v122 row_mirror row_mask:0xf bank_mask:0xf bound_ctrl:1
	s_nop 0
	v_pk_fma_f32 v[166:167], v[10:11], v[122:123], v[166:167] op_sel_hi:[1,0,1]
	v_pk_fma_f32 v[164:165], v[12:13], v[122:123], v[164:165] op_sel_hi:[1,0,1]
	s_waitcnt lgkmcnt(10)
	v_pk_mul_f32 v[114:115], v[166:167], v[22:23]
	v_pk_mul_f32 v[116:117], v[166:167], v[18:19]
	v_pk_fma_f32 v[114:115], v[164:165], v[24:25], v[114:115]
	v_pk_fma_f32 v[116:117], v[164:165], v[20:21], v[116:117]
	v_add_f32_e32 v122, v114, v115
	v_pk_mul_f32 v[118:119], v[82:83], v[34:35] op_sel:[1,0]
	v_add_f32_e32 v218, v116, v117
	ds_read_b128 v[14:17], v124 offset:17408
	ds_read_b128 v[6:9], v124 offset:9216
	ds_read_b128 v[10:13], v124 offset:33792
	ds_read_b128 v[18:21], v124 offset:1024
	ds_read_b128 v[2:5], v124 offset:25600
	ds_read_b128 v[86:89], v125 offset:40976
	v_add_f32_dpp v122, v122, v122 quad_perm:[1,0,3,2] row_mask:0xf bank_mask:0xf bound_ctrl:1
	v_pk_mul_f32 v[120:121], v[82:83], v[36:37] op_sel:[1,0]
	v_add_f32_dpp v210, v210, v210 row_mirror row_mask:0xf bank_mask:0xf bound_ctrl:1
	v_add_f32_dpp v122, v122, v122 quad_perm:[2,3,0,1] row_mask:0xf bank_mask:0xf bound_ctrl:1
	v_pk_fma_f32 v[166:167], v[166:167], v[26:27], v[118:119]
	v_add_f32_dpp v210, v218, v218 row_mirror row_mask:0xf bank_mask:0xc bound_ctrl:1
	v_add_f32_dpp v122, v122, v122 row_half_mirror row_mask:0xf bank_mask:0xf bound_ctrl:1
	v_pk_fma_f32 v[164:165], v[164:165], v[28:29], v[120:121]
	s_nop 0
	v_add_f32_dpp v122, v122, v122 row_mirror row_mask:0xf bank_mask:0xf bound_ctrl:1
	s_nop 0
	v_pk_fma_f32 v[166:167], v[30:31], v[122:123], v[166:167] op_sel_hi:[1,0,1]
	v_pk_fma_f32 v[164:165], v[32:33], v[122:123], v[164:165] op_sel_hi:[1,0,1]
	s_waitcnt lgkmcnt(11)
	v_pk_mul_f32 v[114:115], v[166:167], v[42:43]
	v_pk_mul_f32 v[116:117], v[166:167], v[38:39]
	v_pk_fma_f32 v[114:115], v[164:165], v[44:45], v[114:115]
	v_pk_fma_f32 v[116:117], v[164:165], v[40:41], v[116:117]
	v_add_f32_e32 v122, v114, v115
	v_pk_mul_f32 v[118:119], v[84:85], v[54:55] op_sel_hi:[0,1]
	v_add_f32_e32 v219, v116, v117
	ds_read_b128 v[34:37], v124 offset:17664
	ds_read_b128 v[26:29], v124 offset:9472
	ds_read_b128 v[30:33], v124 offset:34048
	ds_read_b128 v[38:41], v124 offset:1280
	ds_read_b128 v[22:25], v124 offset:25856
	v_add_f32_dpp v122, v122, v122 quad_perm:[1,0,3,2] row_mask:0xf bank_mask:0xf bound_ctrl:1
	v_pk_mul_f32 v[120:121], v[84:85], v[56:57] op_sel_hi:[0,1]
	v_add_f32_dpp v211, v211, v211 row_mirror row_mask:0xf bank_mask:0xf bound_ctrl:1
	v_add_f32_dpp v122, v122, v122 quad_perm:[2,3,0,1] row_mask:0xf bank_mask:0xf bound_ctrl:1
	v_pk_fma_f32 v[166:167], v[166:167], v[46:47], v[118:119]
	v_add_f32_dpp v211, v219, v219 row_mirror row_mask:0xf bank_mask:0xc bound_ctrl:1
	v_add_f32_dpp v122, v122, v122 row_half_mirror row_mask:0xf bank_mask:0xf bound_ctrl:1
	v_pk_fma_f32 v[164:165], v[164:165], v[48:49], v[120:121]
	v_add_f32_dpp v204, v204, v204 row_half_mirror row_mask:0xf bank_mask:0xf bound_ctrl:1
	v_add_f32_dpp v122, v122, v122 row_mirror row_mask:0xf bank_mask:0xf bound_ctrl:1
	v_add_f32_dpp v205, v205, v205 row_half_mirror row_mask:0xf bank_mask:0xf bound_ctrl:1
	v_add_f32_dpp v206, v206, v206 row_half_mirror row_mask:0xf bank_mask:0xf bound_ctrl:1
	v_pk_fma_f32 v[166:167], v[50:51], v[122:123], v[166:167] op_sel_hi:[1,0,1]
	v_pk_fma_f32 v[164:165], v[52:53], v[122:123], v[164:165] op_sel_hi:[1,0,1]
	v_add_f32_dpp v207, v207, v207 row_half_mirror row_mask:0xf bank_mask:0xf bound_ctrl:1
	v_add_f32_dpp v204, v208, v208 row_half_mirror row_mask:0xf bank_mask:0xa bound_ctrl:1
	s_waitcnt lgkmcnt(11)
	v_pk_mul_f32 v[114:115], v[166:167], v[62:63]
	v_pk_mul_f32 v[116:117], v[166:167], v[58:59]
	v_pk_fma_f32 v[114:115], v[164:165], v[64:65], v[114:115]
	v_pk_fma_f32 v[116:117], v[164:165], v[60:61], v[116:117]
	v_add_f32_e32 v122, v114, v115
	v_pk_mul_f32 v[118:119], v[84:85], v[74:75] op_sel:[1,0]
	v_add_f32_e32 v220, v116, v117
	ds_read_b128 v[54:57], v124 offset:17920
	ds_read_b128 v[46:49], v124 offset:9728
	ds_read_b128 v[50:53], v124 offset:34304
	ds_read_b128 v[58:61], v124 offset:1536
	ds_read_b128 v[42:45], v124 offset:26112
	v_add_f32_dpp v122, v122, v122 quad_perm:[1,0,3,2] row_mask:0xf bank_mask:0xf bound_ctrl:1
	v_pk_mul_f32 v[120:121], v[84:85], v[76:77] op_sel:[1,0]
	v_add_f32_dpp v205, v209, v209 row_half_mirror row_mask:0xf bank_mask:0xa bound_ctrl:1
	v_add_f32_dpp v122, v122, v122 quad_perm:[2,3,0,1] row_mask:0xf bank_mask:0xf bound_ctrl:1
	v_pk_fma_f32 v[166:167], v[166:167], v[66:67], v[118:119]
	v_add_f32_dpp v206, v210, v210 row_half_mirror row_mask:0xf bank_mask:0xa bound_ctrl:1
	v_add_f32_dpp v122, v122, v122 row_half_mirror row_mask:0xf bank_mask:0xf bound_ctrl:1
	v_pk_fma_f32 v[164:165], v[164:165], v[68:69], v[120:121]
	v_add_f32_dpp v207, v211, v211 row_half_mirror row_mask:0xf bank_mask:0xa bound_ctrl:1
	v_add_f32_dpp v122, v122, v122 row_mirror row_mask:0xf bank_mask:0xf bound_ctrl:1
	v_add_f32_dpp v204, v204, v204 quad_perm:[1,0,3,2] row_mask:0xf bank_mask:0xf bound_ctrl:1
	v_add_f32_dpp v205, v205, v205 quad_perm:[1,0,3,2] row_mask:0xf bank_mask:0xf bound_ctrl:1
	v_pk_fma_f32 v[166:167], v[70:71], v[122:123], v[166:167] op_sel_hi:[1,0,1]
	v_pk_fma_f32 v[164:165], v[72:73], v[122:123], v[164:165] op_sel_hi:[1,0,1]
	v_add_f32_dpp v206, v206, v206 quad_perm:[1,0,3,2] row_mask:0xf bank_mask:0xf bound_ctrl:1
	v_add_f32_dpp v207, v207, v207 quad_perm:[1,0,3,2] row_mask:0xf bank_mask:0xf bound_ctrl:1
	s_waitcnt lgkmcnt(11)
; #define LAS __attribute__((address_space(3)))
; template <int CTRL> __device__ __forceinline__ float dpp_f(float x) { return __int_as_float(__builtin_amdgcn_update_dpp(0, __float_as_int(x), CTRL, 0xf, 0xf, false)); }
; __device__ __forceinline__ void phase_scan(const Params& p, LAS unsigned char* lds) {
;     ...
;                         for (int u16 = 0; u16 < 16; ++u16) {
;                             const int s = 16 * hb + u16;
;                             const int sn = (s + 1) & 31;
;                             const f32x4 a_n = *(const LAS f32x4*)(sA + sn * 64), w_n = *(const LAS f32x4*)(sW + sn * 64), b_n = *(const LAS f32x4*)(sB + sn * 64);
;                             const f32x4 k_n = *(const LAS f32x4*)(sK + sn * 64), r_n = *(const LAS f32x4*)(sR + sn * 64);
;                             const float v = vq[u16 >> 2][u16 & 3];
;                             const f32x2 vv = {v, v};
;                             f32x2 pp = S01 * (f32x2){a_[0], a_[1]}; pp = S23 * (f32x2){a_[2], a_[3]} + pp;
;                             f32x2 yy = S01 * (f32x2){rp[0], rp[1]}; yy = S23 * (f32x2){rp[2], rp[3]} + yy;
;                             float sa = pp[0] + pp[1], y = yy[0] + yy[1];
;                             sa += dpp_f<0xB1>(sa); y += dpp_f<0xB1>(y);
;                             sa += dpp_f<0x4E>(sa); y += dpp_f<0x4E>(y);
;                             sa += dpp_f<0x141>(sa); y += dpp_f<0x141>(y);
;                             sa += dpp_f<0x140>(sa); y += dpp_f<0x140>(y);
;                             sY[((s - 1) & 31) * 16 + srow] = y;
;                             const f32x2 sv = {sa, sa};
;                             S01 = S01 * (f32x2){w_[0], w_[1]} + vv * (f32x2){k_[0], k_[1]};
;                             S23 = S23 * (f32x2){w_[2], w_[3]} + vv * (f32x2){k_[2], k_[3]};
;                             S01 = sv * (f32x2){b_[0], b_[1]} + S01;
;                             S23 = sv * (f32x2){b_[2], b_[3]} + S23;
;                             rp = r_;
;                             a_ = a_n; w_ = w_n; b_ = b_n; k_ = k_n; r_ = r_n;
;                         }
	v_pk_mul_f32 v[114:115], v[166:167], v[2:3]
	v_pk_mul_f32 v[116:117], v[166:167], v[78:79]
	v_pk_fma_f32 v[114:115], v[164:165], v[4:5], v[114:115]
	v_pk_fma_f32 v[116:117], v[164:165], v[80:81], v[116:117]
	v_add_f32_e32 v122, v114, v115
	s_waitcnt lgkmcnt(10)
	v_pk_mul_f32 v[118:119], v[86:87], v[14:15] op_sel_hi:[0,1]
	v_add_f32_e32 v221, v116, v117
	ds_read_b128 v[74:77], v124 offset:18176
	ds_read_b128 v[66:69], v124 offset:9984
	ds_read_b128 v[70:73], v124 offset:34560
	ds_read_b128 v[78:81], v124 offset:1792
	ds_read_b128 v[62:65], v124 offset:26368
	v_add_f32_dpp v122, v122, v122 quad_perm:[1,0,3,2] row_mask:0xf bank_mask:0xf bound_ctrl:1
	v_pk_mul_f32 v[120:121], v[86:87], v[16:17] op_sel_hi:[0,1]
	v_add_f32_dpp v204, v204, v204 quad_perm:[2,3,0,1] row_mask:0xf bank_mask:0xf bound_ctrl:1
	v_add_f32_dpp v122, v122, v122 quad_perm:[2,3,0,1] row_mask:0xf bank_mask:0xf bound_ctrl:1
	v_pk_fma_f32 v[166:167], v[166:167], v[6:7], v[118:119]
	v_add_f32_dpp v205, v205, v205 quad_perm:[2,3,0,1] row_mask:0xf bank_mask:0xf bound_ctrl:1
	v_add_f32_dpp v122, v122, v122 row_half_mirror row_mask:0xf bank_mask:0xf bound_ctrl:1
	v_pk_fma_f32 v[164:165], v[164:165], v[8:9], v[120:121]
	v_add_f32_dpp v206, v206, v206 quad_perm:[2,3,0,1] row_mask:0xf bank_mask:0xf bound_ctrl:1
	v_add_f32_dpp v122, v122, v122 row_mirror row_mask:0xf bank_mask:0xf bound_ctrl:1
	v_add_f32_dpp v207, v207, v207 quad_perm:[2,3,0,1] row_mask:0xf bank_mask:0xf bound_ctrl:1
	v_cndmask_b32_e64 v202, v204, v205, s[34:35]
	v_pk_fma_f32 v[166:167], v[10:11], v[122:123], v[166:167] op_sel_hi:[1,0,1]
	v_pk_fma_f32 v[164:165], v[12:13], v[122:123], v[164:165] op_sel_hi:[1,0,1]
	v_cndmask_b32_e64 v202, v202, v206, s[56:57]
	v_cndmask_b32_e64 v202, v202, v207, s[98:99]
	s_waitcnt lgkmcnt(10)
	v_pk_mul_f32 v[114:115], v[166:167], v[22:23]
	v_pk_mul_f32 v[116:117], v[166:167], v[18:19]
	v_pk_fma_f32 v[114:115], v[164:165], v[24:25], v[114:115]
	v_pk_fma_f32 v[116:117], v[164:165], v[20:21], v[116:117]
	v_add_f32_e32 v122, v114, v115
	v_pk_mul_f32 v[118:119], v[86:87], v[34:35] op_sel:[1,0]
	v_add_f32_e32 v222, v116, v117
	ds_read_b128 v[14:17], v124 offset:18432
	ds_read_b128 v[6:9], v124 offset:10240
	ds_read_b128 v[10:13], v124 offset:34816
	ds_read_b128 v[18:21], v124 offset:2048
	ds_read_b128 v[2:5], v124 offset:26624
	ds_read_b128 v[90:93], v125 offset:40992
	v_add_f32_dpp v122, v122, v122 quad_perm:[1,0,3,2] row_mask:0xf bank_mask:0xf bound_ctrl:1
	v_pk_mul_f32 v[120:121], v[86:87], v[36:37] op_sel:[1,0]
	v_cvt_f16_f32_e32 v203, v202
	v_add_f32_dpp v122, v122, v122 quad_perm:[2,3,0,1] row_mask:0xf bank_mask:0xf bound_ctrl:1
	v_pk_fma_f32 v[166:167], v[166:167], v[26:27], v[118:119]
	s_mov_b64 exec, s[14:15]
	global_store_short v[128:129], v203, off
	s_mov_b64 exec, -1
	v_add_f32_dpp v122, v122, v122 row_half_mirror row_mask:0xf bank_mask:0xf bound_ctrl:1
	v_pk_fma_f32 v[164:165], v[164:165], v[28:29], v[120:121]
	v_lshl_add_u64 v[128:129], v[128:129], 0, s[100:101]
	v_add_f32_dpp v122, v122, v122 row_mirror row_mask:0xf bank_mask:0xf bound_ctrl:1
	s_nop 0
	v_pk_fma_f32 v[166:167], v[30:31], v[122:123], v[166:167] op_sel_hi:[1,0,1]
	v_pk_fma_f32 v[164:165], v[32:33], v[122:123], v[164:165] op_sel_hi:[1,0,1]
	s_waitcnt lgkmcnt(11)
	v_pk_mul_f32 v[114:115], v[166:167], v[42:43]
	v_pk_mul_f32 v[116:117], v[166:167], v[38:39]
	v_pk_fma_f32 v[114:115], v[164:165], v[44:45], v[114:115]
	v_pk_fma_f32 v[116:117], v[164:165], v[40:41], v[116:117]
	v_add_f32_e32 v122, v114, v115
	v_pk_mul_f32 v[118:119], v[88:89], v[54:55] op_sel_hi:[0,1]
	v_add_f32_e32 v223, v116, v117
	ds_read_b128 v[34:37], v124 offset:18688
	ds_read_b128 v[26:29], v124 offset:10496
	ds_read_b128 v[30:33], v124 offset:35072
	ds_read_b128 v[38:41], v124 offset:2304
	ds_read_b128 v[22:25], v124 offset:26880
	v_add_f32_dpp v122, v122, v122 quad_perm:[1,0,3,2] row_mask:0xf bank_mask:0xf bound_ctrl:1
	v_pk_mul_f32 v[120:121], v[88:89], v[56:57] op_sel_hi:[0,1]
	s_nop 0
	v_add_f32_dpp v122, v122, v122 quad_perm:[2,3,0,1] row_mask:0xf bank_mask:0xf bound_ctrl:1
	v_pk_fma_f32 v[166:167], v[166:167], v[46:47], v[118:119]
	s_nop 0
	v_add_f32_dpp v122, v122, v122 row_half_mirror row_mask:0xf bank_mask:0xf bound_ctrl:1
	v_pk_fma_f32 v[164:165], v[164:165], v[48:49], v[120:121]
	s_nop 0
	v_add_f32_dpp v122, v122, v122 row_mirror row_mask:0xf bank_mask:0xf bound_ctrl:1
	s_nop 0
	v_pk_fma_f32 v[166:167], v[50:51], v[122:123], v[166:167] op_sel_hi:[1,0,1]
	v_pk_fma_f32 v[164:165], v[52:53], v[122:123], v[164:165] op_sel_hi:[1,0,1]
	s_waitcnt lgkmcnt(11)
	v_pk_mul_f32 v[114:115], v[166:167], v[62:63]
	v_pk_mul_f32 v[116:117], v[166:167], v[58:59]
	v_pk_fma_f32 v[114:115], v[164:165], v[64:65], v[114:115]
	v_pk_fma_f32 v[116:117], v[164:165], v[60:61], v[116:117]
	v_add_f32_e32 v122, v114, v115
	v_pk_mul_f32 v[118:119], v[88:89], v[74:75] op_sel:[1,0]
	v_add_f32_e32 v224, v116, v117
	ds_read_b128 v[54:57], v124 offset:18944
	ds_read_b128 v[46:49], v124 offset:10752
	ds_read_b128 v[50:53], v124 offset:35328
	ds_read_b128 v[58:61], v124 offset:2560
	ds_read_b128 v[42:45], v124 offset:27136
	v_add_f32_dpp v122, v122, v122 quad_perm:[1,0,3,2] row_mask:0xf bank_mask:0xf bound_ctrl:1
	v_pk_mul_f32 v[120:121], v[88:89], v[76:77] op_sel:[1,0]
	s_nop 0
	v_add_f32_dpp v122, v122, v122 quad_perm:[2,3,0,1] row_mask:0xf bank_mask:0xf bound_ctrl:1
	v_pk_fma_f32 v[166:167], v[166:167], v[66:67], v[118:119]
	s_nop 0
	v_add_f32_dpp v122, v122, v122 row_half_mirror row_mask:0xf bank_mask:0xf bound_ctrl:1
	v_pk_fma_f32 v[164:165], v[164:165], v[68:69], v[120:121]
	s_nop 0
	v_add_f32_dpp v122, v122, v122 row_mirror row_mask:0xf bank_mask:0xf bound_ctrl:1
	s_nop 0
	v_pk_fma_f32 v[166:167], v[70:71], v[122:123], v[166:167] op_sel_hi:[1,0,1]
	v_pk_fma_f32 v[164:165], v[72:73], v[122:123], v[164:165] op_sel_hi:[1,0,1]
	s_waitcnt lgkmcnt(11)
; #define LAS __attribute__((address_space(3)))
; template <int CTRL> __device__ __forceinline__ float dpp_f(float x) { return __int_as_float(__builtin_amdgcn_update_dpp(0, __float_as_int(x), CTRL, 0xf, 0xf, false)); }
; __device__ __forceinline__ void phase_scan(const Params& p, LAS unsigned char* lds) {
;     ...
;                         for (int u16 = 0; u16 < 16; ++u16) {
;                             const int s = 16 * hb + u16;
;                             const int sn = (s + 1) & 31;
;                             const f32x4 a_n = *(const LAS f32x4*)(sA + sn * 64), w_n = *(const LAS f32x4*)(sW + sn * 64), b_n = *(const LAS f32x4*)(sB + sn * 64);
;                             const f32x4 k_n = *(const LAS f32x4*)(sK + sn * 64), r_n = *(const LAS f32x4*)(sR + sn * 64);
;                             const float v = vq[u16 >> 2][u16 & 3];
;                             const f32x2 vv = {v, v};
;                             f32x2 pp = S01 * (f32x2){a_[0], a_[1]}; pp = S23 * (f32x2){a_[2], a_[3]} + pp;
;                             f32x2 yy = S01 * (f32x2){rp[0], rp[1]}; yy = S23 * (f32x2){rp[2], rp[3]} + yy;
;                             float sa = pp[0] + pp[1], y = yy[0] + yy[1];
;                             sa += dpp_f<0xB1>(sa); y += dpp_f<0xB1>(y);
;                             sa += dpp_f<0x4E>(sa); y += dpp_f<0x4E>(y);
;                             sa += dpp_f<0x141>(sa); y += dpp_f<0x141>(y);
;                             sa += dpp_f<0x140>(sa); y += dpp_f<0x140>(y);
;                             sY[((s - 1) & 31) * 16 + srow] = y;
;                             const f32x2 sv = {sa, sa};
;                             S01 = S01 * (f32x2){w_[0], w_[1]} + vv * (f32x2){k_[0], k_[1]};
;                             S23 = S23 * (f32x2){w_[2], w_[3]} + vv * (f32x2){k_[2], k_[3]};
;                             S01 = sv * (f32x2){b_[0], b_[1]} + S01;
;                             S23 = sv * (f32x2){b_[2], b_[3]} + S23;
;                             rp = r_;
;                             a_ = a_n; w_ = w_n; b_ = b_n; k_ = k_n; r_ = r_n;
;                         }
	v_pk_mul_f32 v[114:115], v[166:167], v[2:3]
	v_pk_mul_f32 v[116:117], v[166:167], v[78:79]
	v_pk_fma_f32 v[114:115], v[164:165], v[4:5], v[114:115]
	v_pk_fma_f32 v[116:117], v[164:165], v[80:81], v[116:117]
	v_add_f32_e32 v122, v114, v115
	s_waitcnt lgkmcnt(10)
	v_pk_mul_f32 v[118:119], v[90:91], v[14:15] op_sel_hi:[0,1]
	v_add_f32_e32 v225, v116, v117
	ds_read_b128 v[74:77], v124 offset:19200
	ds_read_b128 v[66:69], v124 offset:11008
	ds_read_b128 v[70:73], v124 offset:35584
	ds_read_b128 v[78:81], v124 offset:2816
	ds_read_b128 v[62:65], v124 offset:27392
	v_add_f32_dpp v122, v122, v122 quad_perm:[1,0,3,2] row_mask:0xf bank_mask:0xf bound_ctrl:1
	v_pk_mul_f32 v[120:121], v[90:91], v[16:17] op_sel_hi:[0,1]
	s_nop 0
	v_add_f32_dpp v122, v122, v122 quad_perm:[2,3,0,1] row_mask:0xf bank_mask:0xf bound_ctrl:1
	v_pk_fma_f32 v[166:167], v[166:167], v[6:7], v[118:119]
	s_nop 0
	v_add_f32_dpp v122, v122, v122 row_half_mirror row_mask:0xf bank_mask:0xf bound_ctrl:1
	v_pk_fma_f32 v[164:165], v[164:165], v[8:9], v[120:121]
	s_nop 0
	v_add_f32_dpp v122, v122, v122 row_mirror row_mask:0xf bank_mask:0xf bound_ctrl:1
	s_nop 0
	v_pk_fma_f32 v[166:167], v[10:11], v[122:123], v[166:167] op_sel_hi:[1,0,1]
	v_pk_fma_f32 v[164:165], v[12:13], v[122:123], v[164:165] op_sel_hi:[1,0,1]
	s_waitcnt lgkmcnt(10)
	v_pk_mul_f32 v[114:115], v[166:167], v[22:23]
	v_pk_mul_f32 v[116:117], v[166:167], v[18:19]
	v_pk_fma_f32 v[114:115], v[164:165], v[24:25], v[114:115]
	v_pk_fma_f32 v[116:117], v[164:165], v[20:21], v[116:117]
	v_add_f32_e32 v122, v114, v115
	v_pk_mul_f32 v[118:119], v[90:91], v[34:35] op_sel:[1,0]
	v_add_f32_e32 v226, v116, v117
	ds_read_b128 v[14:17], v124 offset:19456
	ds_read_b128 v[6:9], v124 offset:11264
	ds_read_b128 v[10:13], v124 offset:35840
	ds_read_b128 v[18:21], v124 offset:3072
	ds_read_b128 v[2:5], v124 offset:27648
	ds_read_b128 v[94:97], v125 offset:41008
	v_add_f32_dpp v122, v122, v122 quad_perm:[1,0,3,2] row_mask:0xf bank_mask:0xf bound_ctrl:1
	v_pk_mul_f32 v[120:121], v[90:91], v[36:37] op_sel:[1,0]
	s_nop 0
	v_add_f32_dpp v122, v122, v122 quad_perm:[2,3,0,1] row_mask:0xf bank_mask:0xf bound_ctrl:1
	v_pk_fma_f32 v[166:167], v[166:167], v[26:27], v[118:119]
	s_nop 0
	v_add_f32_dpp v122, v122, v122 row_half_mirror row_mask:0xf bank_mask:0xf bound_ctrl:1
	v_pk_fma_f32 v[164:165], v[164:165], v[28:29], v[120:121]
	s_nop 0
	v_add_f32_dpp v122, v122, v122 row_mirror row_mask:0xf bank_mask:0xf bound_ctrl:1
	s_nop 0
	v_pk_fma_f32 v[166:167], v[30:31], v[122:123], v[166:167] op_sel_hi:[1,0,1]
	v_pk_fma_f32 v[164:165], v[32:33], v[122:123], v[164:165] op_sel_hi:[1,0,1]
	s_waitcnt lgkmcnt(11)
	v_pk_mul_f32 v[114:115], v[166:167], v[42:43]
	v_pk_mul_f32 v[116:117], v[166:167], v[38:39]
	v_pk_fma_f32 v[114:115], v[164:165], v[44:45], v[114:115]
	v_pk_fma_f32 v[116:117], v[164:165], v[40:41], v[116:117]
	v_add_f32_e32 v122, v114, v115
	v_pk_mul_f32 v[118:119], v[92:93], v[54:55] op_sel_hi:[0,1]
	v_add_f32_e32 v227, v116, v117
	ds_read_b128 v[34:37], v124 offset:19712
	ds_read_b128 v[26:29], v124 offset:11520
	ds_read_b128 v[30:33], v124 offset:36096
	ds_read_b128 v[38:41], v124 offset:3328
	ds_read_b128 v[22:25], v124 offset:27904
	v_add_f32_dpp v122, v122, v122 quad_perm:[1,0,3,2] row_mask:0xf bank_mask:0xf bound_ctrl:1
	v_pk_mul_f32 v[120:121], v[92:93], v[56:57] op_sel_hi:[0,1]
	s_nop 0
	v_add_f32_dpp v122, v122, v122 quad_perm:[2,3,0,1] row_mask:0xf bank_mask:0xf bound_ctrl:1
	v_pk_fma_f32 v[166:167], v[166:167], v[46:47], v[118:119]
	s_nop 0
	v_add_f32_dpp v122, v122, v122 row_half_mirror row_mask:0xf bank_mask:0xf bound_ctrl:1
	v_pk_fma_f32 v[164:165], v[164:165], v[48:49], v[120:121]
	s_nop 0
	v_add_f32_dpp v122, v122, v122 row_mirror row_mask:0xf bank_mask:0xf bound_ctrl:1
	s_nop 0
	v_pk_fma_f32 v[166:167], v[50:51], v[122:123], v[166:167] op_sel_hi:[1,0,1]
	v_pk_fma_f32 v[164:165], v[52:53], v[122:123], v[164:165] op_sel_hi:[1,0,1]
	s_waitcnt lgkmcnt(11)
	v_pk_mul_f32 v[114:115], v[166:167], v[62:63]
	v_pk_mul_f32 v[116:117], v[166:167], v[58:59]
	v_pk_fma_f32 v[114:115], v[164:165], v[64:65], v[114:115]
	v_pk_fma_f32 v[116:117], v[164:165], v[60:61], v[116:117]
	v_add_f32_e32 v122, v114, v115
	v_pk_mul_f32 v[118:119], v[92:93], v[74:75] op_sel:[1,0]
	v_add_f32_e32 v228, v116, v117
	ds_read_b128 v[54:57], v124 offset:19968
	ds_read_b128 v[46:49], v124 offset:11776
	ds_read_b128 v[50:53], v124 offset:36352
	ds_read_b128 v[58:61], v124 offset:3584
	ds_read_b128 v[42:45], v124 offset:28160
	v_add_f32_dpp v122, v122, v122 quad_perm:[1,0,3,2] row_mask:0xf bank_mask:0xf bound_ctrl:1
	v_pk_mul_f32 v[120:121], v[92:93], v[76:77] op_sel:[1,0]
	v_add_f32_dpp v220, v220, v220 row_mirror row_mask:0xf bank_mask:0xf bound_ctrl:1
	v_add_f32_dpp v122, v122, v122 quad_perm:[2,3,0,1] row_mask:0xf bank_mask:0xf bound_ctrl:1
	v_pk_fma_f32 v[166:167], v[166:167], v[66:67], v[118:119]
	v_add_f32_dpp v220, v228, v228 row_mirror row_mask:0xf bank_mask:0xc bound_ctrl:1
	v_add_f32_dpp v122, v122, v122 row_half_mirror row_mask:0xf bank_mask:0xf bound_ctrl:1
	v_pk_fma_f32 v[164:165], v[164:165], v[68:69], v[120:121]
	s_nop 0
	v_add_f32_dpp v122, v122, v122 row_mirror row_mask:0xf bank_mask:0xf bound_ctrl:1
	s_nop 0
	v_pk_fma_f32 v[166:167], v[70:71], v[122:123], v[166:167] op_sel_hi:[1,0,1]
	v_pk_fma_f32 v[164:165], v[72:73], v[122:123], v[164:165] op_sel_hi:[1,0,1]
	s_waitcnt lgkmcnt(11)
	v_pk_mul_f32 v[114:115], v[166:167], v[2:3]
	v_pk_mul_f32 v[116:117], v[166:167], v[78:79]
	v_pk_fma_f32 v[114:115], v[164:165], v[4:5], v[114:115]
	v_pk_fma_f32 v[116:117], v[164:165], v[80:81], v[116:117]
	v_add_f32_e32 v122, v114, v115
	s_waitcnt lgkmcnt(10)
; #define LAS __attribute__((address_space(3)))
; template <int CTRL> __device__ __forceinline__ float dpp_f(float x) { return __int_as_float(__builtin_amdgcn_update_dpp(0, __float_as_int(x), CTRL, 0xf, 0xf, false)); }
; __device__ __forceinline__ void phase_scan(const Params& p, LAS unsigned char* lds) {
;     ...
;                         for (int u16 = 0; u16 < 16; ++u16) {
;                             const int s = 16 * hb + u16;
;                             const int sn = (s + 1) & 31;
;                             const f32x4 a_n = *(const LAS f32x4*)(sA + sn * 64), w_n = *(const LAS f32x4*)(sW + sn * 64), b_n = *(const LAS f32x4*)(sB + sn * 64);
;                             const f32x4 k_n = *(const LAS f32x4*)(sK + sn * 64), r_n = *(const LAS f32x4*)(sR + sn * 64);
;                             const float v = vq[u16 >> 2][u16 & 3];
;                             const f32x2 vv = {v, v};
;                             f32x2 pp = S01 * (f32x2){a_[0], a_[1]}; pp = S23 * (f32x2){a_[2], a_[3]} + pp;
;                             f32x2 yy = S01 * (f32x2){rp[0], rp[1]}; yy = S23 * (f32x2){rp[2], rp[3]} + yy;
;                             float sa = pp[0] + pp[1], y = yy[0] + yy[1];
;                             sa += dpp_f<0xB1>(sa); y += dpp_f<0xB1>(y);
;                             sa += dpp_f<0x4E>(sa); y += dpp_f<0x4E>(y);
;                             sa += dpp_f<0x141>(sa); y += dpp_f<0x141>(y);
;                             sa += dpp_f<0x140>(sa); y += dpp_f<0x140>(y);
;                             sY[((s - 1) & 31) * 16 + srow] = y;
;                             const f32x2 sv = {sa, sa};
;                             S01 = S01 * (f32x2){w_[0], w_[1]} + vv * (f32x2){k_[0], k_[1]};
;                             S23 = S23 * (f32x2){w_[2], w_[3]} + vv * (f32x2){k_[2], k_[3]};
;                             S01 = sv * (f32x2){b_[0], b_[1]} + S01;
;                             S23 = sv * (f32x2){b_[2], b_[3]} + S23;
;                             rp = r_;
;                             a_ = a_n; w_ = w_n; b_ = b_n; k_ = k_n; r_ = r_n;
;                         }
	v_pk_mul_f32 v[118:119], v[94:95], v[14:15] op_sel_hi:[0,1]
	v_add_f32_e32 v229, v116, v117
	ds_read_b128 v[74:77], v124 offset:20224
	ds_read_b128 v[66:69], v124 offset:12032
	ds_read_b128 v[70:73], v124 offset:36608
	ds_read_b128 v[78:81], v124 offset:3840
	ds_read_b128 v[62:65], v124 offset:28416
	v_add_f32_dpp v122, v122, v122 quad_perm:[1,0,3,2] row_mask:0xf bank_mask:0xf bound_ctrl:1
	v_pk_mul_f32 v[120:121], v[94:95], v[16:17] op_sel_hi:[0,1]
	v_add_f32_dpp v221, v221, v221 row_mirror row_mask:0xf bank_mask:0xf bound_ctrl:1
	v_add_f32_dpp v122, v122, v122 quad_perm:[2,3,0,1] row_mask:0xf bank_mask:0xf bound_ctrl:1
	v_pk_fma_f32 v[166:167], v[166:167], v[6:7], v[118:119]
	v_add_f32_dpp v221, v229, v229 row_mirror row_mask:0xf bank_mask:0xc bound_ctrl:1
	v_add_f32_dpp v122, v122, v122 row_half_mirror row_mask:0xf bank_mask:0xf bound_ctrl:1
	v_pk_fma_f32 v[164:165], v[164:165], v[8:9], v[120:121]
	s_nop 0
	v_add_f32_dpp v122, v122, v122 row_mirror row_mask:0xf bank_mask:0xf bound_ctrl:1
	s_nop 0
	v_pk_fma_f32 v[166:167], v[10:11], v[122:123], v[166:167] op_sel_hi:[1,0,1]
	v_pk_fma_f32 v[164:165], v[12:13], v[122:123], v[164:165] op_sel_hi:[1,0,1]
	s_waitcnt lgkmcnt(10)
	v_pk_mul_f32 v[114:115], v[166:167], v[22:23]
	v_pk_mul_f32 v[116:117], v[166:167], v[18:19]
	v_pk_fma_f32 v[114:115], v[164:165], v[24:25], v[114:115]
	v_pk_fma_f32 v[116:117], v[164:165], v[20:21], v[116:117]
	v_add_f32_e32 v122, v114, v115
	v_pk_mul_f32 v[118:119], v[94:95], v[34:35] op_sel:[1,0]
	v_add_f32_e32 v230, v116, v117
	ds_read_b128 v[14:17], v124 offset:20480
	ds_read_b128 v[6:9], v124 offset:12288
	ds_read_b128 v[10:13], v124 offset:36864
	ds_read_b128 v[18:21], v124 offset:4096
	ds_read_b128 v[2:5], v124 offset:28672
	ds_read_b128 v[98:101], v125 offset:41024
	v_add_f32_dpp v122, v122, v122 quad_perm:[1,0,3,2] row_mask:0xf bank_mask:0xf bound_ctrl:1
	v_pk_mul_f32 v[120:121], v[94:95], v[36:37] op_sel:[1,0]
	v_add_f32_dpp v222, v222, v222 row_mirror row_mask:0xf bank_mask:0xf bound_ctrl:1
	v_add_f32_dpp v122, v122, v122 quad_perm:[2,3,0,1] row_mask:0xf bank_mask:0xf bound_ctrl:1
	v_pk_fma_f32 v[166:167], v[166:167], v[26:27], v[118:119]
	v_add_f32_dpp v222, v230, v230 row_mirror row_mask:0xf bank_mask:0xc bound_ctrl:1
	v_add_f32_dpp v122, v122, v122 row_half_mirror row_mask:0xf bank_mask:0xf bound_ctrl:1
	v_pk_fma_f32 v[164:165], v[164:165], v[28:29], v[120:121]
	s_nop 0
	v_add_f32_dpp v122, v122, v122 row_mirror row_mask:0xf bank_mask:0xf bound_ctrl:1
	s_nop 0
	v_pk_fma_f32 v[166:167], v[30:31], v[122:123], v[166:167] op_sel_hi:[1,0,1]
	v_pk_fma_f32 v[164:165], v[32:33], v[122:123], v[164:165] op_sel_hi:[1,0,1]
	s_waitcnt lgkmcnt(11)
	v_pk_mul_f32 v[114:115], v[166:167], v[42:43]
	v_pk_mul_f32 v[116:117], v[166:167], v[38:39]
	v_pk_fma_f32 v[114:115], v[164:165], v[44:45], v[114:115]
	v_pk_fma_f32 v[116:117], v[164:165], v[40:41], v[116:117]
	v_add_f32_e32 v122, v114, v115
	v_pk_mul_f32 v[118:119], v[96:97], v[54:55] op_sel_hi:[0,1]
	v_add_f32_e32 v231, v116, v117
	ds_read_b128 v[34:37], v124 offset:20736
	ds_read_b128 v[26:29], v124 offset:12544
	ds_read_b128 v[30:33], v124 offset:37120
	ds_read_b128 v[38:41], v124 offset:4352
	ds_read_b128 v[22:25], v124 offset:28928
	v_add_f32_dpp v122, v122, v122 quad_perm:[1,0,3,2] row_mask:0xf bank_mask:0xf bound_ctrl:1
	v_pk_mul_f32 v[120:121], v[96:97], v[56:57] op_sel_hi:[0,1]
	v_add_f32_dpp v223, v223, v223 row_mirror row_mask:0xf bank_mask:0xf bound_ctrl:1
	v_add_f32_dpp v122, v122, v122 quad_perm:[2,3,0,1] row_mask:0xf bank_mask:0xf bound_ctrl:1
	v_pk_fma_f32 v[166:167], v[166:167], v[46:47], v[118:119]
	v_add_f32_dpp v223, v231, v231 row_mirror row_mask:0xf bank_mask:0xc bound_ctrl:1
	v_add_f32_dpp v122, v122, v122 row_half_mirror row_mask:0xf bank_mask:0xf bound_ctrl:1
	v_pk_fma_f32 v[164:165], v[164:165], v[48:49], v[120:121]
	s_nop 0
	v_add_f32_dpp v122, v122, v122 row_mirror row_mask:0xf bank_mask:0xf bound_ctrl:1
	s_nop 0
	v_pk_fma_f32 v[166:167], v[50:51], v[122:123], v[166:167] op_sel_hi:[1,0,1]
	v_pk_fma_f32 v[164:165], v[52:53], v[122:123], v[164:165] op_sel_hi:[1,0,1]
	s_waitcnt lgkmcnt(11)
	v_pk_mul_f32 v[114:115], v[166:167], v[62:63]
	v_pk_mul_f32 v[116:117], v[166:167], v[58:59]
	v_pk_fma_f32 v[114:115], v[164:165], v[64:65], v[114:115]
	v_pk_fma_f32 v[116:117], v[164:165], v[60:61], v[116:117]
	v_add_f32_e32 v122, v114, v115
	v_pk_mul_f32 v[118:119], v[96:97], v[74:75] op_sel:[1,0]
	v_add_f32_e32 v232, v116, v117
	ds_read_b128 v[54:57], v124 offset:20992
	ds_read_b128 v[46:49], v124 offset:12800
	ds_read_b128 v[50:53], v124 offset:37376
	ds_read_b128 v[58:61], v124 offset:4608
	ds_read_b128 v[42:45], v124 offset:29184
	v_add_f32_dpp v122, v122, v122 quad_perm:[1,0,3,2] row_mask:0xf bank_mask:0xf bound_ctrl:1
	v_pk_mul_f32 v[120:121], v[96:97], v[76:77] op_sel:[1,0]
	v_add_f32_dpp v224, v224, v224 row_mirror row_mask:0xf bank_mask:0xf bound_ctrl:1
	v_add_f32_dpp v122, v122, v122 quad_perm:[2,3,0,1] row_mask:0xf bank_mask:0xf bound_ctrl:1
	v_pk_fma_f32 v[166:167], v[166:167], v[66:67], v[118:119]
	v_add_f32_dpp v224, v232, v232 row_mirror row_mask:0xf bank_mask:0xc bound_ctrl:1
	v_add_f32_dpp v122, v122, v122 row_half_mirror row_mask:0xf bank_mask:0xf bound_ctrl:1
	v_pk_fma_f32 v[164:165], v[164:165], v[68:69], v[120:121]
	s_nop 0
	v_add_f32_dpp v122, v122, v122 row_mirror row_mask:0xf bank_mask:0xf bound_ctrl:1
	s_nop 0
	v_pk_fma_f32 v[166:167], v[70:71], v[122:123], v[166:167] op_sel_hi:[1,0,1]
	v_pk_fma_f32 v[164:165], v[72:73], v[122:123], v[164:165] op_sel_hi:[1,0,1]
	s_waitcnt lgkmcnt(11)
; #define LAS __attribute__((address_space(3)))
; template <int CTRL> __device__ __forceinline__ float dpp_f(float x) { return __int_as_float(__builtin_amdgcn_update_dpp(0, __float_as_int(x), CTRL, 0xf, 0xf, false)); }
; __device__ __forceinline__ void phase_scan(const Params& p, LAS unsigned char* lds) {
;     ...
;                         for (int u16 = 0; u16 < 16; ++u16) {
;                             const int s = 16 * hb + u16;
;                             const int sn = (s + 1) & 31;
;                             const f32x4 a_n = *(const LAS f32x4*)(sA + sn * 64), w_n = *(const LAS f32x4*)(sW + sn * 64), b_n = *(const LAS f32x4*)(sB + sn * 64);
;                             const f32x4 k_n = *(const LAS f32x4*)(sK + sn * 64), r_n = *(const LAS f32x4*)(sR + sn * 64);
;                             const float v = vq[u16 >> 2][u16 & 3];
;                             const f32x2 vv = {v, v};
;                             f32x2 pp = S01 * (f32x2){a_[0], a_[1]}; pp = S23 * (f32x2){a_[2], a_[3]} + pp;
;                             f32x2 yy = S01 * (f32x2){rp[0], rp[1]}; yy = S23 * (f32x2){rp[2], rp[3]} + yy;
;                             float sa = pp[0] + pp[1], y = yy[0] + yy[1];
;                             sa += dpp_f<0xB1>(sa); y += dpp_f<0xB1>(y);
;                             sa += dpp_f<0x4E>(sa); y += dpp_f<0x4E>(y);
;                             sa += dpp_f<0x141>(sa); y += dpp_f<0x141>(y);
;                             sa += dpp_f<0x140>(sa); y += dpp_f<0x140>(y);
;                             sY[((s - 1) & 31) * 16 + srow] = y;
;                             const f32x2 sv = {sa, sa};
;                             S01 = S01 * (f32x2){w_[0], w_[1]} + vv * (f32x2){k_[0], k_[1]};
;                             S23 = S23 * (f32x2){w_[2], w_[3]} + vv * (f32x2){k_[2], k_[3]};
;                             S01 = sv * (f32x2){b_[0], b_[1]} + S01;
;                             S23 = sv * (f32x2){b_[2], b_[3]} + S23;
;                             rp = r_;
;                             a_ = a_n; w_ = w_n; b_ = b_n; k_ = k_n; r_ = r_n;
;                         }
	v_pk_mul_f32 v[114:115], v[166:167], v[2:3]
	v_pk_mul_f32 v[116:117], v[166:167], v[78:79]
	v_pk_fma_f32 v[114:115], v[164:165], v[4:5], v[114:115]
	v_pk_fma_f32 v[116:117], v[164:165], v[80:81], v[116:117]
	v_add_f32_e32 v122, v114, v115
	s_waitcnt lgkmcnt(10)
	v_pk_mul_f32 v[118:119], v[98:99], v[14:15] op_sel_hi:[0,1]
	v_add_f32_e32 v233, v116, v117
	ds_read_b128 v[74:77], v124 offset:21248
	ds_read_b128 v[66:69], v124 offset:13056
	ds_read_b128 v[70:73], v124 offset:37632
	ds_read_b128 v[78:81], v124 offset:4864
	ds_read_b128 v[62:65], v124 offset:29440
	v_add_f32_dpp v122, v122, v122 quad_perm:[1,0,3,2] row_mask:0xf bank_mask:0xf bound_ctrl:1
	v_pk_mul_f32 v[120:121], v[98:99], v[16:17] op_sel_hi:[0,1]
	v_add_f32_dpp v225, v225, v225 row_mirror row_mask:0xf bank_mask:0xf bound_ctrl:1
	v_add_f32_dpp v122, v122, v122 quad_perm:[2,3,0,1] row_mask:0xf bank_mask:0xf bound_ctrl:1
	v_pk_fma_f32 v[166:167], v[166:167], v[6:7], v[118:119]
	v_add_f32_dpp v225, v233, v233 row_mirror row_mask:0xf bank_mask:0xc bound_ctrl:1
	v_add_f32_dpp v122, v122, v122 row_half_mirror row_mask:0xf bank_mask:0xf bound_ctrl:1
	v_pk_fma_f32 v[164:165], v[164:165], v[8:9], v[120:121]
	s_nop 0
	v_add_f32_dpp v122, v122, v122 row_mirror row_mask:0xf bank_mask:0xf bound_ctrl:1
	s_nop 0
	v_pk_fma_f32 v[166:167], v[10:11], v[122:123], v[166:167] op_sel_hi:[1,0,1]
	v_pk_fma_f32 v[164:165], v[12:13], v[122:123], v[164:165] op_sel_hi:[1,0,1]
	s_waitcnt lgkmcnt(10)
	v_pk_mul_f32 v[114:115], v[166:167], v[22:23]
	v_pk_mul_f32 v[116:117], v[166:167], v[18:19]
	v_pk_fma_f32 v[114:115], v[164:165], v[24:25], v[114:115]
	v_pk_fma_f32 v[116:117], v[164:165], v[20:21], v[116:117]
	v_add_f32_e32 v122, v114, v115
	v_pk_mul_f32 v[118:119], v[98:99], v[34:35] op_sel:[1,0]
	v_add_f32_e32 v234, v116, v117
	ds_read_b128 v[14:17], v124 offset:21504
	ds_read_b128 v[6:9], v124 offset:13312
	ds_read_b128 v[10:13], v124 offset:37888
	ds_read_b128 v[18:21], v124 offset:5120
	ds_read_b128 v[2:5], v124 offset:29696
	ds_read_b128 v[102:105], v125 offset:41040
	v_add_f32_dpp v122, v122, v122 quad_perm:[1,0,3,2] row_mask:0xf bank_mask:0xf bound_ctrl:1
	v_pk_mul_f32 v[120:121], v[98:99], v[36:37] op_sel:[1,0]
	v_add_f32_dpp v226, v226, v226 row_mirror row_mask:0xf bank_mask:0xf bound_ctrl:1
	v_add_f32_dpp v122, v122, v122 quad_perm:[2,3,0,1] row_mask:0xf bank_mask:0xf bound_ctrl:1
	v_pk_fma_f32 v[166:167], v[166:167], v[26:27], v[118:119]
	v_add_f32_dpp v226, v234, v234 row_mirror row_mask:0xf bank_mask:0xc bound_ctrl:1
	v_add_f32_dpp v122, v122, v122 row_half_mirror row_mask:0xf bank_mask:0xf bound_ctrl:1
	v_pk_fma_f32 v[164:165], v[164:165], v[28:29], v[120:121]
	s_nop 0
	v_add_f32_dpp v122, v122, v122 row_mirror row_mask:0xf bank_mask:0xf bound_ctrl:1
	s_nop 0
	v_pk_fma_f32 v[166:167], v[30:31], v[122:123], v[166:167] op_sel_hi:[1,0,1]
	v_pk_fma_f32 v[164:165], v[32:33], v[122:123], v[164:165] op_sel_hi:[1,0,1]
	s_waitcnt lgkmcnt(11)
	v_pk_mul_f32 v[114:115], v[166:167], v[42:43]
	v_pk_mul_f32 v[116:117], v[166:167], v[38:39]
	v_pk_fma_f32 v[114:115], v[164:165], v[44:45], v[114:115]
	v_pk_fma_f32 v[116:117], v[164:165], v[40:41], v[116:117]
	v_add_f32_e32 v122, v114, v115
	v_pk_mul_f32 v[118:119], v[100:101], v[54:55] op_sel_hi:[0,1]
	v_add_f32_e32 v235, v116, v117
	ds_read_b128 v[34:37], v124 offset:21760
	ds_read_b128 v[26:29], v124 offset:13568
	ds_read_b128 v[30:33], v124 offset:38144
	ds_read_b128 v[38:41], v124 offset:5376
	ds_read_b128 v[22:25], v124 offset:29952
	v_add_f32_dpp v122, v122, v122 quad_perm:[1,0,3,2] row_mask:0xf bank_mask:0xf bound_ctrl:1
	v_pk_mul_f32 v[120:121], v[100:101], v[56:57] op_sel_hi:[0,1]
	v_add_f32_dpp v227, v227, v227 row_mirror row_mask:0xf bank_mask:0xf bound_ctrl:1
	v_add_f32_dpp v122, v122, v122 quad_perm:[2,3,0,1] row_mask:0xf bank_mask:0xf bound_ctrl:1
	v_pk_fma_f32 v[166:167], v[166:167], v[46:47], v[118:119]
	v_add_f32_dpp v227, v235, v235 row_mirror row_mask:0xf bank_mask:0xc bound_ctrl:1
	v_add_f32_dpp v122, v122, v122 row_half_mirror row_mask:0xf bank_mask:0xf bound_ctrl:1
	v_pk_fma_f32 v[164:165], v[164:165], v[48:49], v[120:121]
	v_add_f32_dpp v220, v220, v220 row_half_mirror row_mask:0xf bank_mask:0xf bound_ctrl:1
	v_add_f32_dpp v122, v122, v122 row_mirror row_mask:0xf bank_mask:0xf bound_ctrl:1
	v_add_f32_dpp v221, v221, v221 row_half_mirror row_mask:0xf bank_mask:0xf bound_ctrl:1
	v_add_f32_dpp v222, v222, v222 row_half_mirror row_mask:0xf bank_mask:0xf bound_ctrl:1
	v_pk_fma_f32 v[166:167], v[50:51], v[122:123], v[166:167] op_sel_hi:[1,0,1]
	v_pk_fma_f32 v[164:165], v[52:53], v[122:123], v[164:165] op_sel_hi:[1,0,1]
	v_add_f32_dpp v223, v223, v223 row_half_mirror row_mask:0xf bank_mask:0xf bound_ctrl:1
	v_add_f32_dpp v220, v224, v224 row_half_mirror row_mask:0xf bank_mask:0xa bound_ctrl:1
	s_waitcnt lgkmcnt(11)
; #define LAS __attribute__((address_space(3)))
; template <int CTRL> __device__ __forceinline__ float dpp_f(float x) { return __int_as_float(__builtin_amdgcn_update_dpp(0, __float_as_int(x), CTRL, 0xf, 0xf, false)); }
; __device__ __forceinline__ void phase_scan(const Params& p, LAS unsigned char* lds) {
;     ...
;                         for (int u16 = 0; u16 < 16; ++u16) {
;                             const int s = 16 * hb + u16;
;                             const int sn = (s + 1) & 31;
;                             const f32x4 a_n = *(const LAS f32x4*)(sA + sn * 64), w_n = *(const LAS f32x4*)(sW + sn * 64), b_n = *(const LAS f32x4*)(sB + sn * 64);
;                             const f32x4 k_n = *(const LAS f32x4*)(sK + sn * 64), r_n = *(const LAS f32x4*)(sR + sn * 64);
;                             const float v = vq[u16 >> 2][u16 & 3];
;                             const f32x2 vv = {v, v};
;                             f32x2 pp = S01 * (f32x2){a_[0], a_[1]}; pp = S23 * (f32x2){a_[2], a_[3]} + pp;
;                             f32x2 yy = S01 * (f32x2){rp[0], rp[1]}; yy = S23 * (f32x2){rp[2], rp[3]} + yy;
;                             float sa = pp[0] + pp[1], y = yy[0] + yy[1];
;                             sa += dpp_f<0xB1>(sa); y += dpp_f<0xB1>(y);
;                             sa += dpp_f<0x4E>(sa); y += dpp_f<0x4E>(y);
;                             sa += dpp_f<0x141>(sa); y += dpp_f<0x141>(y);
;                             sa += dpp_f<0x140>(sa); y += dpp_f<0x140>(y);
;                             sY[((s - 1) & 31) * 16 + srow] = y;
;                             const f32x2 sv = {sa, sa};
;                             S01 = S01 * (f32x2){w_[0], w_[1]} + vv * (f32x2){k_[0], k_[1]};
;                             S23 = S23 * (f32x2){w_[2], w_[3]} + vv * (f32x2){k_[2], k_[3]};
;                             S01 = sv * (f32x2){b_[0], b_[1]} + S01;
;                             S23 = sv * (f32x2){b_[2], b_[3]} + S23;
;                             rp = r_;
;                             a_ = a_n; w_ = w_n; b_ = b_n; k_ = k_n; r_ = r_n;
;                         }
	v_pk_mul_f32 v[114:115], v[166:167], v[62:63]
	v_pk_mul_f32 v[116:117], v[166:167], v[58:59]
	v_pk_fma_f32 v[114:115], v[164:165], v[64:65], v[114:115]
	v_pk_fma_f32 v[116:117], v[164:165], v[60:61], v[116:117]
	v_add_f32_e32 v122, v114, v115
	v_pk_mul_f32 v[118:119], v[100:101], v[74:75] op_sel:[1,0]
	v_add_f32_e32 v204, v116, v117
	ds_read_b128 v[54:57], v124 offset:22016
	ds_read_b128 v[46:49], v124 offset:13824
	ds_read_b128 v[50:53], v124 offset:38400
	ds_read_b128 v[58:61], v124 offset:5632
	ds_read_b128 v[42:45], v124 offset:30208
	v_add_f32_dpp v122, v122, v122 quad_perm:[1,0,3,2] row_mask:0xf bank_mask:0xf bound_ctrl:1
	v_pk_mul_f32 v[120:121], v[100:101], v[76:77] op_sel:[1,0]
	v_add_f32_dpp v221, v225, v225 row_half_mirror row_mask:0xf bank_mask:0xa bound_ctrl:1
	v_add_f32_dpp v122, v122, v122 quad_perm:[2,3,0,1] row_mask:0xf bank_mask:0xf bound_ctrl:1
	v_pk_fma_f32 v[166:167], v[166:167], v[66:67], v[118:119]
	v_add_f32_dpp v222, v226, v226 row_half_mirror row_mask:0xf bank_mask:0xa bound_ctrl:1
	v_add_f32_dpp v122, v122, v122 row_half_mirror row_mask:0xf bank_mask:0xf bound_ctrl:1
	v_pk_fma_f32 v[164:165], v[164:165], v[68:69], v[120:121]
	v_add_f32_dpp v223, v227, v227 row_half_mirror row_mask:0xf bank_mask:0xa bound_ctrl:1
	v_add_f32_dpp v122, v122, v122 row_mirror row_mask:0xf bank_mask:0xf bound_ctrl:1
	v_add_f32_dpp v220, v220, v220 quad_perm:[1,0,3,2] row_mask:0xf bank_mask:0xf bound_ctrl:1
	v_add_f32_dpp v221, v221, v221 quad_perm:[1,0,3,2] row_mask:0xf bank_mask:0xf bound_ctrl:1
	v_pk_fma_f32 v[166:167], v[70:71], v[122:123], v[166:167] op_sel_hi:[1,0,1]
	v_pk_fma_f32 v[164:165], v[72:73], v[122:123], v[164:165] op_sel_hi:[1,0,1]
	v_add_f32_dpp v222, v222, v222 quad_perm:[1,0,3,2] row_mask:0xf bank_mask:0xf bound_ctrl:1
	v_add_f32_dpp v223, v223, v223 quad_perm:[1,0,3,2] row_mask:0xf bank_mask:0xf bound_ctrl:1
	s_waitcnt lgkmcnt(11)
	v_pk_mul_f32 v[114:115], v[166:167], v[2:3]
	v_pk_mul_f32 v[116:117], v[166:167], v[78:79]
	v_pk_fma_f32 v[114:115], v[164:165], v[4:5], v[114:115]
	v_pk_fma_f32 v[116:117], v[164:165], v[80:81], v[116:117]
	v_add_f32_e32 v122, v114, v115
	s_waitcnt lgkmcnt(10)
	v_pk_mul_f32 v[118:119], v[102:103], v[14:15] op_sel_hi:[0,1]
	v_add_f32_e32 v205, v116, v117
	ds_read_b128 v[74:77], v124 offset:22272
	ds_read_b128 v[66:69], v124 offset:14080
	ds_read_b128 v[70:73], v124 offset:38656
	ds_read_b128 v[78:81], v124 offset:5888
	ds_read_b128 v[62:65], v124 offset:30464
	v_add_f32_dpp v122, v122, v122 quad_perm:[1,0,3,2] row_mask:0xf bank_mask:0xf bound_ctrl:1
	v_pk_mul_f32 v[120:121], v[102:103], v[16:17] op_sel_hi:[0,1]
	v_add_f32_dpp v220, v220, v220 quad_perm:[2,3,0,1] row_mask:0xf bank_mask:0xf bound_ctrl:1
	v_add_f32_dpp v122, v122, v122 quad_perm:[2,3,0,1] row_mask:0xf bank_mask:0xf bound_ctrl:1
	v_pk_fma_f32 v[166:167], v[166:167], v[6:7], v[118:119]
	v_add_f32_dpp v221, v221, v221 quad_perm:[2,3,0,1] row_mask:0xf bank_mask:0xf bound_ctrl:1
	v_add_f32_dpp v122, v122, v122 row_half_mirror row_mask:0xf bank_mask:0xf bound_ctrl:1
	v_pk_fma_f32 v[164:165], v[164:165], v[8:9], v[120:121]
	v_add_f32_dpp v222, v222, v222 quad_perm:[2,3,0,1] row_mask:0xf bank_mask:0xf bound_ctrl:1
	v_add_f32_dpp v122, v122, v122 row_mirror row_mask:0xf bank_mask:0xf bound_ctrl:1
	v_add_f32_dpp v223, v223, v223 quad_perm:[2,3,0,1] row_mask:0xf bank_mask:0xf bound_ctrl:1
	v_cndmask_b32_e64 v202, v220, v221, s[34:35]
	v_pk_fma_f32 v[166:167], v[10:11], v[122:123], v[166:167] op_sel_hi:[1,0,1]
	v_pk_fma_f32 v[164:165], v[12:13], v[122:123], v[164:165] op_sel_hi:[1,0,1]
	v_cndmask_b32_e64 v202, v202, v222, s[56:57]
	v_cndmask_b32_e64 v202, v202, v223, s[98:99]
	s_waitcnt lgkmcnt(10)
	v_pk_mul_f32 v[114:115], v[166:167], v[22:23]
	v_pk_mul_f32 v[116:117], v[166:167], v[18:19]
	v_pk_fma_f32 v[114:115], v[164:165], v[24:25], v[114:115]
	v_pk_fma_f32 v[116:117], v[164:165], v[20:21], v[116:117]
	v_add_f32_e32 v122, v114, v115
	v_pk_mul_f32 v[118:119], v[102:103], v[34:35] op_sel:[1,0]
	v_add_f32_e32 v206, v116, v117
	ds_read_b128 v[14:17], v124 offset:22528
	ds_read_b128 v[6:9], v124 offset:14336
	ds_read_b128 v[10:13], v124 offset:38912
	ds_read_b128 v[18:21], v124 offset:6144
	ds_read_b128 v[2:5], v124 offset:30720
	ds_read_b128 v[106:109], v125 offset:41056
	v_add_f32_dpp v122, v122, v122 quad_perm:[1,0,3,2] row_mask:0xf bank_mask:0xf bound_ctrl:1
	v_pk_mul_f32 v[120:121], v[102:103], v[36:37] op_sel:[1,0]
	v_cvt_f16_f32_e32 v203, v202
	v_add_f32_dpp v122, v122, v122 quad_perm:[2,3,0,1] row_mask:0xf bank_mask:0xf bound_ctrl:1
	v_pk_fma_f32 v[166:167], v[166:167], v[26:27], v[118:119]
	global_store_short v[126:127], v203, off
	v_add_f32_dpp v122, v122, v122 row_half_mirror row_mask:0xf bank_mask:0xf bound_ctrl:1
	v_pk_fma_f32 v[164:165], v[164:165], v[28:29], v[120:121]
	v_lshl_add_u64 v[126:127], v[126:127], 0, s[100:101]
	v_add_f32_dpp v122, v122, v122 row_mirror row_mask:0xf bank_mask:0xf bound_ctrl:1
	s_nop 0
	v_pk_fma_f32 v[166:167], v[30:31], v[122:123], v[166:167] op_sel_hi:[1,0,1]
	v_pk_fma_f32 v[164:165], v[32:33], v[122:123], v[164:165] op_sel_hi:[1,0,1]
	s_waitcnt lgkmcnt(11)
; #define LAS __attribute__((address_space(3)))
; template <int CTRL> __device__ __forceinline__ float dpp_f(float x) { return __int_as_float(__builtin_amdgcn_update_dpp(0, __float_as_int(x), CTRL, 0xf, 0xf, false)); }
; __device__ __forceinline__ void phase_scan(const Params& p, LAS unsigned char* lds) {
;     ...
;                         for (int u16 = 0; u16 < 16; ++u16) {
;                             const int s = 16 * hb + u16;
;                             const int sn = (s + 1) & 31;
;                             const f32x4 a_n = *(const LAS f32x4*)(sA + sn * 64), w_n = *(const LAS f32x4*)(sW + sn * 64), b_n = *(const LAS f32x4*)(sB + sn * 64);
;                             const f32x4 k_n = *(const LAS f32x4*)(sK + sn * 64), r_n = *(const LAS f32x4*)(sR + sn * 64);
;                             const float v = vq[u16 >> 2][u16 & 3];
;                             const f32x2 vv = {v, v};
;                             f32x2 pp = S01 * (f32x2){a_[0], a_[1]}; pp = S23 * (f32x2){a_[2], a_[3]} + pp;
;                             f32x2 yy = S01 * (f32x2){rp[0], rp[1]}; yy = S23 * (f32x2){rp[2], rp[3]} + yy;
;                             float sa = pp[0] + pp[1], y = yy[0] + yy[1];
;                             sa += dpp_f<0xB1>(sa); y += dpp_f<0xB1>(y);
;                             sa += dpp_f<0x4E>(sa); y += dpp_f<0x4E>(y);
;                             sa += dpp_f<0x141>(sa); y += dpp_f<0x141>(y);
;                             sa += dpp_f<0x140>(sa); y += dpp_f<0x140>(y);
;                             sY[((s - 1) & 31) * 16 + srow] = y;
;                             const f32x2 sv = {sa, sa};
;                             S01 = S01 * (f32x2){w_[0], w_[1]} + vv * (f32x2){k_[0], k_[1]};
;                             S23 = S23 * (f32x2){w_[2], w_[3]} + vv * (f32x2){k_[2], k_[3]};
;                             S01 = sv * (f32x2){b_[0], b_[1]} + S01;
;                             S23 = sv * (f32x2){b_[2], b_[3]} + S23;
;                             rp = r_;
;                             a_ = a_n; w_ = w_n; b_ = b_n; k_ = k_n; r_ = r_n;
;                         }
	v_pk_mul_f32 v[114:115], v[166:167], v[42:43]
	v_pk_mul_f32 v[116:117], v[166:167], v[38:39]
	v_pk_fma_f32 v[114:115], v[164:165], v[44:45], v[114:115]
	v_pk_fma_f32 v[116:117], v[164:165], v[40:41], v[116:117]
	v_add_f32_e32 v122, v114, v115
	v_pk_mul_f32 v[118:119], v[104:105], v[54:55] op_sel_hi:[0,1]
	v_add_f32_e32 v207, v116, v117
	ds_read_b128 v[34:37], v124 offset:22784
	ds_read_b128 v[26:29], v124 offset:14592
	ds_read_b128 v[30:33], v124 offset:39168
	ds_read_b128 v[38:41], v124 offset:6400
	ds_read_b128 v[22:25], v124 offset:30976
	v_add_f32_dpp v122, v122, v122 quad_perm:[1,0,3,2] row_mask:0xf bank_mask:0xf bound_ctrl:1
	v_pk_mul_f32 v[120:121], v[104:105], v[56:57] op_sel_hi:[0,1]
	s_nop 0
	v_add_f32_dpp v122, v122, v122 quad_perm:[2,3,0,1] row_mask:0xf bank_mask:0xf bound_ctrl:1
	v_pk_fma_f32 v[166:167], v[166:167], v[46:47], v[118:119]
	s_nop 0
	v_add_f32_dpp v122, v122, v122 row_half_mirror row_mask:0xf bank_mask:0xf bound_ctrl:1
	v_pk_fma_f32 v[164:165], v[164:165], v[48:49], v[120:121]
	s_nop 0
	v_add_f32_dpp v122, v122, v122 row_mirror row_mask:0xf bank_mask:0xf bound_ctrl:1
	s_nop 0
	v_pk_fma_f32 v[166:167], v[50:51], v[122:123], v[166:167] op_sel_hi:[1,0,1]
	v_pk_fma_f32 v[164:165], v[52:53], v[122:123], v[164:165] op_sel_hi:[1,0,1]
	s_waitcnt lgkmcnt(11)
	v_pk_mul_f32 v[114:115], v[166:167], v[62:63]
	v_pk_mul_f32 v[116:117], v[166:167], v[58:59]
	v_pk_fma_f32 v[114:115], v[164:165], v[64:65], v[114:115]
	v_pk_fma_f32 v[116:117], v[164:165], v[60:61], v[116:117]
	v_add_f32_e32 v122, v114, v115
	v_pk_mul_f32 v[118:119], v[104:105], v[74:75] op_sel:[1,0]
	v_add_f32_e32 v208, v116, v117
	ds_read_b128 v[54:57], v124 offset:23040
	ds_read_b128 v[46:49], v124 offset:14848
	ds_read_b128 v[50:53], v124 offset:39424
	ds_read_b128 v[58:61], v124 offset:6656
	ds_read_b128 v[42:45], v124 offset:31232
	v_add_f32_dpp v122, v122, v122 quad_perm:[1,0,3,2] row_mask:0xf bank_mask:0xf bound_ctrl:1
	v_pk_mul_f32 v[120:121], v[104:105], v[76:77] op_sel:[1,0]
	s_nop 0
	v_add_f32_dpp v122, v122, v122 quad_perm:[2,3,0,1] row_mask:0xf bank_mask:0xf bound_ctrl:1
	v_pk_fma_f32 v[166:167], v[166:167], v[66:67], v[118:119]
	s_nop 0
	v_add_f32_dpp v122, v122, v122 row_half_mirror row_mask:0xf bank_mask:0xf bound_ctrl:1
	v_pk_fma_f32 v[164:165], v[164:165], v[68:69], v[120:121]
	s_nop 0
	v_add_f32_dpp v122, v122, v122 row_mirror row_mask:0xf bank_mask:0xf bound_ctrl:1
	s_nop 0
	v_pk_fma_f32 v[166:167], v[70:71], v[122:123], v[166:167] op_sel_hi:[1,0,1]
	v_pk_fma_f32 v[164:165], v[72:73], v[122:123], v[164:165] op_sel_hi:[1,0,1]
	s_waitcnt lgkmcnt(11)
	v_pk_mul_f32 v[114:115], v[166:167], v[2:3]
	v_pk_mul_f32 v[116:117], v[166:167], v[78:79]
	v_pk_fma_f32 v[114:115], v[164:165], v[4:5], v[114:115]
	v_pk_fma_f32 v[116:117], v[164:165], v[80:81], v[116:117]
	v_add_f32_e32 v122, v114, v115
	s_waitcnt lgkmcnt(10)
	v_pk_mul_f32 v[118:119], v[106:107], v[14:15] op_sel_hi:[0,1]
	v_add_f32_e32 v209, v116, v117
	ds_read_b128 v[74:77], v124 offset:23296
	ds_read_b128 v[66:69], v124 offset:15104
	ds_read_b128 v[70:73], v124 offset:39680
	ds_read_b128 v[78:81], v124 offset:6912
	ds_read_b128 v[62:65], v124 offset:31488
	v_add_f32_dpp v122, v122, v122 quad_perm:[1,0,3,2] row_mask:0xf bank_mask:0xf bound_ctrl:1
	v_pk_mul_f32 v[120:121], v[106:107], v[16:17] op_sel_hi:[0,1]
	s_nop 0
	v_add_f32_dpp v122, v122, v122 quad_perm:[2,3,0,1] row_mask:0xf bank_mask:0xf bound_ctrl:1
	v_pk_fma_f32 v[166:167], v[166:167], v[6:7], v[118:119]
	s_nop 0
	v_add_f32_dpp v122, v122, v122 row_half_mirror row_mask:0xf bank_mask:0xf bound_ctrl:1
	v_pk_fma_f32 v[164:165], v[164:165], v[8:9], v[120:121]
	s_nop 0
	v_add_f32_dpp v122, v122, v122 row_mirror row_mask:0xf bank_mask:0xf bound_ctrl:1
	s_nop 0
	v_pk_fma_f32 v[166:167], v[10:11], v[122:123], v[166:167] op_sel_hi:[1,0,1]
	v_pk_fma_f32 v[164:165], v[12:13], v[122:123], v[164:165] op_sel_hi:[1,0,1]
	s_waitcnt lgkmcnt(10)
	v_pk_mul_f32 v[114:115], v[166:167], v[22:23]
	v_pk_mul_f32 v[116:117], v[166:167], v[18:19]
	v_pk_fma_f32 v[114:115], v[164:165], v[24:25], v[114:115]
	v_pk_fma_f32 v[116:117], v[164:165], v[20:21], v[116:117]
	v_add_f32_e32 v122, v114, v115
	v_pk_mul_f32 v[118:119], v[106:107], v[34:35] op_sel:[1,0]
	v_add_f32_e32 v210, v116, v117
	ds_read_b128 v[14:17], v124 offset:23552
	ds_read_b128 v[6:9], v124 offset:15360
	ds_read_b128 v[10:13], v124 offset:39936
	ds_read_b128 v[18:21], v124 offset:7168
	ds_read_b128 v[2:5], v124 offset:31744
	ds_read_b128 v[110:113], v125 offset:41072
	v_add_f32_dpp v122, v122, v122 quad_perm:[1,0,3,2] row_mask:0xf bank_mask:0xf bound_ctrl:1
	v_pk_mul_f32 v[120:121], v[106:107], v[36:37] op_sel:[1,0]
	s_nop 0
	v_add_f32_dpp v122, v122, v122 quad_perm:[2,3,0,1] row_mask:0xf bank_mask:0xf bound_ctrl:1
	v_pk_fma_f32 v[166:167], v[166:167], v[26:27], v[118:119]
	s_nop 0
	v_add_f32_dpp v122, v122, v122 row_half_mirror row_mask:0xf bank_mask:0xf bound_ctrl:1
	v_pk_fma_f32 v[164:165], v[164:165], v[28:29], v[120:121]
	s_nop 0
	v_add_f32_dpp v122, v122, v122 row_mirror row_mask:0xf bank_mask:0xf bound_ctrl:1
	s_nop 0
	v_pk_fma_f32 v[166:167], v[30:31], v[122:123], v[166:167] op_sel_hi:[1,0,1]
	v_pk_fma_f32 v[164:165], v[32:33], v[122:123], v[164:165] op_sel_hi:[1,0,1]
	s_waitcnt lgkmcnt(11)
; #define LAS __attribute__((address_space(3)))
; __device__ __forceinline__ void phase_scan(const Params& p, LAS unsigned char* lds) {
;     ...
;                         for (int u16 = 0; u16 < 16; ++u16) {
;                             const int s = 16 * hb + u16;
;                             const int sn = (s + 1) & 31;
;                             const f32x4 a_n = *(const LAS f32x4*)(sA + sn * 64), w_n = *(const LAS f32x4*)(sW + sn * 64), b_n = *(const LAS f32x4*)(sB + sn * 64);
;                             const f32x4 k_n = *(const LAS f32x4*)(sK + sn * 64), r_n = *(const LAS f32x4*)(sR + sn * 64);
;                             const float v = vq[u16 >> 2][u16 & 3];
;                             const f32x2 vv = {v, v};
;                             f32x2 pp = S01 * (f32x2){a_[0], a_[1]}; pp = S23 * (f32x2){a_[2], a_[3]} + pp;
;                             f32x2 yy = S01 * (f32x2){rp[0], rp[1]}; yy = S23 * (f32x2){rp[2], rp[3]} + yy;
;                             float sa = pp[0] + pp[1], y = yy[0] + yy[1];
;                             sa += dpp_f<0xB1>(sa); y += dpp_f<0xB1>(y);
;                             sa += dpp_f<0x4E>(sa); y += dpp_f<0x4E>(y);
;                             sa += dpp_f<0x141>(sa); y += dpp_f<0x141>(y);
;                             sa += dpp_f<0x140>(sa); y += dpp_f<0x140>(y);
;                             sY[((s - 1) & 31) * 16 + srow] = y;
;                             const f32x2 sv = {sa, sa};
;                             S01 = S01 * (f32x2){w_[0], w_[1]} + vv * (f32x2){k_[0], k_[1]};
;                             S23 = S23 * (f32x2){w_[2], w_[3]} + vv * (f32x2){k_[2], k_[3]};
;                             S01 = sv * (f32x2){b_[0], b_[1]} + S01;
;                             S23 = sv * (f32x2){b_[2], b_[3]} + S23;
;                             rp = r_;
;                             a_ = a_n; w_ = w_n; b_ = b_n; k_ = k_n; r_ = r_n;
;                         }
; #pragma unroll
;                         for (int u = 0; u < 4; ++u) vq[u] = vn[u];
;                     }
;                     { f32x2 yy = S01 * (f32x2){rp[0], rp[1]}; yy = S23 * (f32x2){rp[2], rp[3]} + yy; sY[31 * 16 + srow] = red16(yy[0] + yy[1]); }
;                     __builtin_amdgcn_s_setprio(0);
	v_pk_mul_f32 v[114:115], v[166:167], v[42:43]
	v_pk_mul_f32 v[116:117], v[166:167], v[38:39]
	v_pk_fma_f32 v[114:115], v[164:165], v[44:45], v[114:115]
	v_pk_fma_f32 v[116:117], v[164:165], v[40:41], v[116:117]
	v_add_f32_e32 v122, v114, v115
	v_pk_mul_f32 v[118:119], v[108:109], v[54:55] op_sel_hi:[0,1]
	v_add_f32_e32 v211, v116, v117
	ds_read_b128 v[34:37], v124 offset:23808
	ds_read_b128 v[26:29], v124 offset:15616
	ds_read_b128 v[30:33], v124 offset:40192
	ds_read_b128 v[38:41], v124 offset:7424
	ds_read_b128 v[22:25], v124 offset:32000
	v_add_f32_dpp v122, v122, v122 quad_perm:[1,0,3,2] row_mask:0xf bank_mask:0xf bound_ctrl:1
	v_pk_mul_f32 v[120:121], v[108:109], v[56:57] op_sel_hi:[0,1]
	s_nop 0
	v_add_f32_dpp v122, v122, v122 quad_perm:[2,3,0,1] row_mask:0xf bank_mask:0xf bound_ctrl:1
	v_pk_fma_f32 v[166:167], v[166:167], v[46:47], v[118:119]
	s_nop 0
	v_add_f32_dpp v122, v122, v122 row_half_mirror row_mask:0xf bank_mask:0xf bound_ctrl:1
	v_pk_fma_f32 v[164:165], v[164:165], v[48:49], v[120:121]
	s_nop 0
	v_add_f32_dpp v122, v122, v122 row_mirror row_mask:0xf bank_mask:0xf bound_ctrl:1
	s_nop 0
	v_pk_fma_f32 v[166:167], v[50:51], v[122:123], v[166:167] op_sel_hi:[1,0,1]
	v_pk_fma_f32 v[164:165], v[52:53], v[122:123], v[164:165] op_sel_hi:[1,0,1]
	s_waitcnt lgkmcnt(11)
	v_pk_mul_f32 v[114:115], v[166:167], v[62:63]
	v_pk_mul_f32 v[116:117], v[166:167], v[58:59]
	v_pk_fma_f32 v[114:115], v[164:165], v[64:65], v[114:115]
	v_pk_fma_f32 v[116:117], v[164:165], v[60:61], v[116:117]
	v_add_f32_e32 v122, v114, v115
	v_pk_mul_f32 v[118:119], v[108:109], v[74:75] op_sel:[1,0]
	v_add_f32_e32 v212, v116, v117
	ds_read_b128 v[54:57], v124 offset:24064
	ds_read_b128 v[46:49], v124 offset:15872
	ds_read_b128 v[50:53], v124 offset:40448
	ds_read_b128 v[58:61], v124 offset:7680
	ds_read_b128 v[42:45], v124 offset:32256
	v_add_f32_dpp v122, v122, v122 quad_perm:[1,0,3,2] row_mask:0xf bank_mask:0xf bound_ctrl:1
	v_pk_mul_f32 v[120:121], v[108:109], v[76:77] op_sel:[1,0]
	s_nop 0
	v_add_f32_dpp v122, v122, v122 quad_perm:[2,3,0,1] row_mask:0xf bank_mask:0xf bound_ctrl:1
	v_pk_fma_f32 v[166:167], v[166:167], v[66:67], v[118:119]
	s_nop 0
	v_add_f32_dpp v122, v122, v122 row_half_mirror row_mask:0xf bank_mask:0xf bound_ctrl:1
	v_pk_fma_f32 v[164:165], v[164:165], v[68:69], v[120:121]
	s_nop 0
	v_add_f32_dpp v122, v122, v122 row_mirror row_mask:0xf bank_mask:0xf bound_ctrl:1
	s_nop 0
	v_pk_fma_f32 v[166:167], v[70:71], v[122:123], v[166:167] op_sel_hi:[1,0,1]
	v_pk_fma_f32 v[164:165], v[72:73], v[122:123], v[164:165] op_sel_hi:[1,0,1]
	s_waitcnt lgkmcnt(11)
	v_pk_mul_f32 v[114:115], v[166:167], v[2:3]
	v_pk_mul_f32 v[116:117], v[166:167], v[78:79]
	v_pk_fma_f32 v[114:115], v[164:165], v[4:5], v[114:115]
	v_pk_fma_f32 v[116:117], v[164:165], v[80:81], v[116:117]
	v_add_f32_e32 v122, v114, v115
	s_waitcnt lgkmcnt(10)
	v_pk_mul_f32 v[118:119], v[110:111], v[14:15] op_sel_hi:[0,1]
	v_add_f32_e32 v213, v116, v117
	ds_read_b128 v[74:77], v124 offset:24320
	ds_read_b128 v[66:69], v124 offset:16128
	ds_read_b128 v[70:73], v124 offset:40704
	ds_read_b128 v[78:81], v124 offset:7936
	ds_read_b128 v[62:65], v124 offset:32512
	v_add_f32_dpp v122, v122, v122 quad_perm:[1,0,3,2] row_mask:0xf bank_mask:0xf bound_ctrl:1
	v_pk_mul_f32 v[120:121], v[110:111], v[16:17] op_sel_hi:[0,1]
	s_nop 0
	v_add_f32_dpp v122, v122, v122 quad_perm:[2,3,0,1] row_mask:0xf bank_mask:0xf bound_ctrl:1
	v_pk_fma_f32 v[166:167], v[166:167], v[6:7], v[118:119]
	s_nop 0
	v_add_f32_dpp v122, v122, v122 row_half_mirror row_mask:0xf bank_mask:0xf bound_ctrl:1
	v_pk_fma_f32 v[164:165], v[164:165], v[8:9], v[120:121]
	s_nop 0
	v_add_f32_dpp v122, v122, v122 row_mirror row_mask:0xf bank_mask:0xf bound_ctrl:1
	s_nop 0
	v_pk_fma_f32 v[166:167], v[10:11], v[122:123], v[166:167] op_sel_hi:[1,0,1]
	v_pk_fma_f32 v[164:165], v[12:13], v[122:123], v[164:165] op_sel_hi:[1,0,1]
	s_setprio 0
	s_branch .LBB0_603
